# attention phase: one static s_setprio 1 for the younger wave half (waves 4-7), reset before the closing barrier
# baseline (speedup 1.0000x reference)
; #define LAS __attribute__((address_space(3)))
; __device__ __forceinline__ int fresh_tid() { int t = threadIdx.x; asm volatile("" : "+v"(t)); return t; }
; __device__ __forceinline__ int v_rd_base(int lane) { return ((lane & 3) << 3) | (((lane >> 2) & 3) << 6) | (((lane >> 4) & 1) << 5) | (((lane >> 5) & 1) << 8); }
; __device__ __forceinline__ void attn_phase(unsigned char* ws_, unsigned char* outb, const float* rpb, LAS unsigned char* lds, int wg, int nwg, int grp) {
;     const int tid = fresh_tid(), wid = __builtin_amdgcn_readfirstlane(tid >> 6), lane = tid & 63, r32 = lane & 31, hi = lane >> 5;
;     const bf16_t* qkv = (const bf16_t*)(ws_ + OFF_X + (size_t)grp * XG_BYTES);
;     LAS unsigned char* V_lds = lds; LAS unsigned char* K_lds = lds + 32768;
;     LAS float* wsf = (LAS float*)(lds + 65536) + wid * 64; LAS float* li_l = wsf; LAS float* al_l = wsf + 32;
;     LAS unsigned char* oL = lds + 69888 + wid * 8192;
;     LAS unsigned char* qL = oL + lane * 16;
;     LAS float* rpbL = (LAS float*)(lds + 65536 + 2048);
;     const int krow = tid >> 4, kcs = ((tid & 15) ^ (krow & 7)) * 8;
;     int vk0, vk1, vc0, vc1;
;     { const int D0 = tid * 16, D1 = D0 + 8192;
;       const int st0 = D0 >> 9, kk0 = (st0 >> 2) * 8 + ((D0 & 511) >> 6); vk0 = (kk0 & ~0xC) | ((kk0 & 4) << 1) | ((kk0 & 8) >> 1); vc0 = (st0 & 3) * 32 + ((D0 & 63) >> 4) * 8;
;       const int st1 = D1 >> 9, kk1 = (st1 >> 2) * 8 + ((D1 & 511) >> 6); vk1 = (kk1 & ~0xC) | ((kk1 & 4) << 1) | ((kk1 & 8) >> 1); vc1 = (st1 & 3) * 32 + ((D1 & 63) >> 4) * 8; }
;     const unsigned dmaw = (unsigned)wid * 1024u;
;     const int vrd = v_rd_base(lane);
;     const int qb = wid >> 1, half = wid & 1, iq = 32 * half + r32;
;     int vw = wg;
;     int gj = -1;
;     if (vw >= 128) return;
.LBB0_467:
	s_or_b64 exec, exec, s[2:3]
	s_waitcnt lgkmcnt(0)
	s_barrier
	s_load_dwordx2 s[2:3], s[0:1], 0xb0
	v_mov_b32_e32 v160, v158
	s_cmpk_gt_i32 s35, 0x7f
	s_waitcnt lgkmcnt(0)
	v_writelane_b32 v232, s2, 24
	s_nop 1
	v_writelane_b32 v232, s3, 25
	v_readfirstlane_b32 s2, v160
	s_cbranch_scc1 .LBB0_555
	s_cmp_gt_u32 s2, 0xff
	s_cbranch_scc0 .Latt_prio_skip
	s_setprio 1
; #define LAS __attribute__((address_space(3)))
; __device__ __forceinline__ int fresh_tid() { int t = threadIdx.x; asm volatile("" : "+v"(t)); return t; }
; __device__ __forceinline__ int v_rd_base(int lane) { return ((lane & 3) << 3) | (((lane >> 2) & 3) << 6) | (((lane >> 4) & 1) << 5) | (((lane >> 5) & 1) << 8); }
; #define NEXT_ITEM(ok) do { ok = true; if (gj > 8) { vw += nwg; gj = -1; } \
;         if (vw >= 128) ok = false; \
;         else if (gj < 0) { att_decode(grp * 128 + vw, cur); gj = 0; } \
;         else { const int ix_ = 9 * vw + gj, br_ = ix_ / 384; att_decode(ATT_NA_ITEMS + br_ * 768 + grp * 384 + (ix_ - br_ * 384), cur); if (cur.canmerge && gj + 1 <= 8) cur.nb4 = 2; gj += cur.nb4; } } while (0)
; __device__ __forceinline__ void attn_phase(unsigned char* ws_, unsigned char* outb, const float* rpb, LAS unsigned char* lds, int wg, int nwg, int grp) {
;     const int tid = fresh_tid(), wid = __builtin_amdgcn_readfirstlane(tid >> 6), lane = tid & 63, r32 = lane & 31, hi = lane >> 5;
;     const bf16_t* qkv = (const bf16_t*)(ws_ + OFF_X + (size_t)grp * XG_BYTES);
;     LAS unsigned char* V_lds = lds; LAS unsigned char* K_lds = lds + 32768;
;     LAS float* wsf = (LAS float*)(lds + 65536) + wid * 64; LAS float* li_l = wsf; LAS float* al_l = wsf + 32;
;     LAS unsigned char* oL = lds + 69888 + wid * 8192;
;     LAS unsigned char* qL = oL + lane * 16;
;     LAS float* rpbL = (LAS float*)(lds + 65536 + 2048);
;     const int krow = tid >> 4, kcs = ((tid & 15) ^ (krow & 7)) * 8;
;     int vk0, vk1, vc0, vc1;
;     { const int D0 = tid * 16, D1 = D0 + 8192;
;       const int st0 = D0 >> 9, kk0 = (st0 >> 2) * 8 + ((D0 & 511) >> 6); vk0 = (kk0 & ~0xC) | ((kk0 & 4) << 1) | ((kk0 & 8) >> 1); vc0 = (st0 & 3) * 32 + ((D0 & 63) >> 4) * 8;
;       const int st1 = D1 >> 9, kk1 = (st1 >> 2) * 8 + ((D1 & 511) >> 6); vk1 = (kk1 & ~0xC) | ((kk1 & 4) << 1) | ((kk1 & 8) >> 1); vc1 = (st1 & 3) * 32 + ((D1 & 63) >> 4) * 8; }
;     const unsigned dmaw = (unsigned)wid * 1024u;
;     const int vrd = v_rd_base(lane);
;     const int qb = wid >> 1, half = wid & 1, iq = 32 * half + r32;
;     int vw = wg;
;     int gj = -1;
;     if (vw >= 128) return;
;     AttItem cur;
;     ...
;     bf16x8 qreg[8];
;     ...
;     bool ok0; NEXT_ITEM(ok0);
;     LOADQ(cur, cur.n0 + qb); DMA_TILE(cur, att_tlo(cur), 0);
.Latt_prio_skip:
	v_ashrrev_i32_e32 v162, 4, v160
	v_lshlrev_b32_e32 v39, 4, v160
	v_lshrrev_b32_e32 v3, 1, v162
	v_add_u32_e32 v0, 0x2000, v39
	v_lshrrev_b32_e32 v2, 1, v160
	v_and_b32_e32 v3, 4, v3
	v_writelane_b32 v232, s68, 26
	s_ashr_i32 s9, s2, 6
	v_bfe_u32 v1, v160, 2, 2
	v_and_b32_e32 v2, 8, v2
	v_and_or_b32 v3, v162, -16, v3
	v_ashrrev_i32_e32 v0, 8, v0
	s_ashr_i32 s37, s2, 7
	s_and_b32 s2, s2, 0x3fffffc0
	v_writelane_b32 v232, s69, 27
	v_or3_b32 v163, v3, v1, v2
	v_lshrrev_b32_e32 v3, 1, v0
	s_lshl_b32 s2, s2, 2
	v_and_b32_e32 v33, 63, v160
	v_and_b32_e32 v3, 4, v3
	s_add_i32 s2, s2, 0
	v_readlane_b32 s34, v232, 0
	v_lshlrev_b32_e32 v161, 4, v33
	v_and_or_b32 v0, v0, -16, v3
	s_add_i32 s33, s2, 0x10000
	s_lshl_b32 s2, s34, 7
	v_or3_b32 v164, v0, v1, v2
	v_lshlrev_b32_e32 v0, 3, v33
	v_and_b32_e32 v1, 0xc0, v161
	v_lshlrev_b32_e32 v2, 1, v160
	v_writelane_b32 v232, s2, 28
	s_add_i32 s7, s2, s35
	s_lshl_b32 s2, s35, 2
	v_and_or_b32 v1, v0, 24, v1
	v_and_b32_e32 v2, 32, v2
	v_and_b32_e32 v0, 0x100, v0
	s_and_b32 s23, s9, 1
	s_and_b32 s31, s2, 0x7c
	v_and_b32_e32 v35, 31, v160
	v_or3_b32 v165, v1, v2, v0
	s_lshl_b32 s28, s23, 5
	v_lshlrev_b32_e32 v46, 3, v160
	v_and_b32_e32 v0, 0x60, v160
	v_readlane_b32 s38, v232, 12
	v_sub_u32_e64 v40, s31, 4 clamp
	v_or_b32_e32 v166, s28, v35
	v_and_or_b32 v32, v46, 24, v0
	v_and_b32_e32 v0, 15, v160
	s_add_i32 s2, s37, s31
	v_readlane_b32 s39, v232, 13
	v_lshlrev_b32_e32 v40, 6, v40
	v_bitop3_b32 v42, v162, v0, 7 bitop3:0x6c
	s_bfe_u32 s54, s74, 0x20005
	v_lshl_or_b32 v0, s2, 6, v166
	s_movk_i32 s29, 0x3000
	v_mov_b64_e32 v[36:37], s[38:39]
	v_add_u32_e32 v41, v162, v40
	s_mov_b32 s3, 0
	s_lshl_b32 s6, s9, 10
	v_bfe_u32 v47, v160, 5, 1
	v_mad_i64_i32 v[0:1], s[4:5], v0, s29, v[36:37]
	s_lshl_b32 s2, s54, 8
	v_mov_b32_e32 v137, 0
	v_add_u32_e32 v48, v163, v40
	v_add_u32_e32 v49, v164, v40
	v_mad_i64_i32 v[40:41], s[4:5], v41, s29, v[36:37]
	v_lshlrev_b32_e32 v34, 3, v42
	v_lshl_add_u64 v[0:1], v[0:1], 0, s[2:3]
	v_lshlrev_b32_e32 v136, 4, v47
	v_lshl_add_u64 v[40:41], v[40:41], 0, s[2:3]
	v_lshlrev_b32_e32 v42, 4, v42
	v_mov_b32_e32 v43, v137
	s_add_i32 s36, s6, 0
	v_lshl_add_u64 v[28:29], v[0:1], 0, v[136:137]
	v_lshl_add_u64 v[40:41], v[40:41], 0, v[42:43]
	s_mov_b64 s[4:5], 0x400
	s_add_i32 s40, s36, 0x8000
	global_load_dwordx4 v[0:3], v[28:29], off
	global_load_dwordx4 v[4:7], v[28:29], off offset:32
	global_load_dwordx4 v[8:11], v[28:29], off offset:64
	global_load_dwordx4 v[12:15], v[28:29], off offset:96
	global_load_dwordx4 v[16:19], v[28:29], off offset:128
	global_load_dwordx4 v[20:23], v[28:29], off offset:160
	global_load_dwordx4 v[24:27], v[28:29], off offset:192
	s_nop 0
	global_load_dwordx4 v[28:31], v[28:29], off offset:224
	v_lshl_add_u64 v[44:45], v[40:41], 0, s[4:5]
	s_mov_b32 m0, s40
	s_mov_b64 s[4:5], 0x60400
	s_add_i32 s41, s36, 0xa000
	global_load_lds_dwordx4 v[44:45], off
	v_lshl_add_u64 v[40:41], v[40:41], 0, s[4:5]
	s_mov_b32 m0, s41
	s_ashr_i32 s58, s7, 7
	global_load_lds_dwordx4 v[40:41], off
	v_mad_i64_i32 v[40:41], s[4:5], v48, s29, v[36:37]
	v_lshl_add_u64 v[40:41], v[40:41], 0, s[2:3]
	v_lshlrev_b32_e32 v44, 1, v32
	v_mov_b32_e32 v45, v137
	v_mad_i64_i32 v[36:37], s[6:7], v49, s29, v[36:37]
	v_lshl_add_u64 v[40:41], v[40:41], 0, v[44:45]
	s_mov_b64 s[4:5], 0x800
	v_lshl_add_u64 v[36:37], v[36:37], 0, s[2:3]
	v_lshl_add_u64 v[40:41], v[40:41], 0, s[4:5]
	s_mov_b32 m0, s36
	v_lshl_add_u64 v[36:37], v[36:37], 0, v[44:45]
	s_add_i32 s22, s36, 0x2000
	global_load_lds_dwordx4 v[40:41], off
	v_lshl_add_u64 v[36:37], v[36:37], 0, s[4:5]
	s_mov_b32 m0, s22
	s_lshl_b32 s10, s9, 13
	global_load_lds_dwordx4 v[36:37], off
	v_lshl_add_u64 v[138:139], s[38:39], 0, v[42:43]
	v_lshl_add_u64 v[140:141], s[38:39], 0, v[44:45]
	v_lshl_add_u64 v[142:143], s[38:39], 0, v[136:137]
	s_load_dwordx2 s[38:39], s[0:1], 0xb0
	s_add_i32 s27, s10, 0
	s_lshl_b32 s8, s54, 7
	s_add_i32 s27, s27, 0x11100
	s_or_b32 s66, s8, 0x200
	s_or_b32 s68, s8, 0x400
	s_movk_i32 s2, 0x231
	s_add_u32 s42, s16, 0xb900000
	v_cmp_gt_i32_e64 s[4:5], s2, v160
	s_addc_u32 s43, s17, 0
	s_lshl_b32 s2, s34, 26
	s_waitcnt lgkmcnt(0)
	s_add_u32 s44, s38, s2
	s_addc_u32 s45, s39, 0
	s_lshl_b32 s2, s34, 25
	v_readlane_b32 s38, v232, 16
	v_cmp_gt_u32_e64 s[6:7], 32, v33
	v_lshlrev_b32_e32 v33, 2, v47
	s_add_u32 s46, s38, s2
	s_movk_i32 s2, 0x70
	s_movk_i32 s30, 0x60
	v_lshl_add_u32 v167, v35, 2, s33
	v_lshl_add_u32 v168, v35, 1, s27
	v_sub_u32_e32 v169, v35, v33
	v_lshlrev_b32_e32 v170, 8, v35
	v_and_b32_e32 v35, 0x70, v39
	v_bitop3_b32 v171, v136, v39, s2 bitop3:0x78
	s_movk_i32 s2, 0xa0
	s_movk_i32 s11, 0xc0
	v_bitop3_b32 v174, v136, v35, s30 bitop3:0x36
	s_movk_i32 s30, 0x80
	v_bitop3_b32 v176, v136, v35, s2 bitop3:0x36
	s_movk_i32 s2, 0xe0
	v_bitop3_b32 v172, v136, v35, 32 bitop3:0x36
	v_bitop3_b32 v173, v136, v35, 64 bitop3:0x36
	v_bitop3_b32 v175, v136, v35, s30 bitop3:0x36
	v_bitop3_b32 v177, v136, v35, s11 bitop3:0x36
	v_bitop3_b32 v178, v136, v35, s2 bitop3:0x36
	v_sub_u32_e64 v35, v166, 8 clamp
	v_min_u32_e32 v35, 48, v35
	v_readlane_b32 s39, v232, 17
	v_sub_u32_e32 v180, v35, v33
	v_sub_u32_e32 v181, v166, v33
	v_lshlrev_b32_e32 v33, 2, v166
	s_addc_u32 s47, s39, 0
	v_sub_u32_e32 v33, 0, v33
	s_mov_b32 s2, 0x10c24
	v_and_b32_e32 v40, 0x300, v161
	v_and_b32_e32 v41, 0xf0, v39
	s_bitcmp1_b32 s9, 0
	v_add3_u32 v200, v33, v136, s2
	v_lshl_add_u32 v33, v160, 2, 0
	v_lshlrev_b32_e32 v38, 3, v47
	v_bfe_u32 v37, v160, 4, 2
	v_and_b32_e32 v36, 0x78, v46
	s_cselect_b64 s[50:51], -1, 0
	s_cmp_eq_u32 s23, 0
	v_lshlrev_b32_e32 v183, 10, v47
	v_add_u32_e32 v201, 0x10800, v33
	v_or3_b32 v33, s10, v40, v41
	s_mov_b32 s48, 1
	s_cselect_b64 s[52:53], -1, 0
	v_add_u32_e32 v179, 0, v170
	v_add_u32_e32 v182, s33, v136
	v_or_b32_e32 v184, 0x100, v183
	v_or_b32_e32 v185, 0x200, v183
	v_or_b32_e32 v186, 0x300, v183
	v_or_b32_e32 v187, 0x800, v183
	v_or_b32_e32 v188, 0x900, v183
	v_or_b32_e32 v189, 0xa00, v183
	v_or_b32_e32 v190, 0xb00, v183
	v_or_b32_e32 v191, 0x1000, v183
	v_or_b32_e32 v192, 0x1100, v183
	v_or_b32_e32 v193, 0x1200, v183
	v_or_b32_e32 v194, 0x1300, v183
	v_or_b32_e32 v195, 0x1800, v183
	v_or_b32_e32 v196, 0x1900, v183
	v_or_b32_e32 v197, 0x1a00, v183
	v_or_b32_e32 v198, 0x1b00, v183
	v_or_b32_e32 v199, s28, v37
	v_add_u32_e32 v202, 0, v33
	s_mov_b32 s23, 0x600000
	s_mov_b64 s[56:57], 0xc00000
	s_movk_i32 s11, 0xffe0
	v_lshlrev_b32_e32 v136, 1, v36
	v_lshlrev_b32_e32 v144, 1, v38
	v_lshlrev_b32_e32 v146, 1, v34
	v_lshlrev_b32_e32 v148, 1, v32
	v_mov_b32_e32 v203, 0xf149f2ca
	v_mov_b32_e32 v204, 0x600000
	v_mov_b32_e32 v205, 0x60000
	s_mov_b32 s33, 0
	s_mov_b32 s28, 1
	s_mov_b32 s2, s3
	s_mov_b32 s55, 1
	s_mov_b32 s10, s3
	s_branch .LBB0_471

; __device__ __forceinline__ unsigned xb_ld(unsigned* p)              { return __hip_atomic_load(p, __ATOMIC_RELAXED, __HIP_MEMORY_SCOPE_AGENT); }
; __device__ __forceinline__ unsigned xb_add(unsigned* p, unsigned v) { return __hip_atomic_fetch_add(p, v, __ATOMIC_RELAXED, __HIP_MEMORY_SCOPE_AGENT); }
; __device__ __forceinline__ void xcd_barrier_complete(unsigned* bar, unsigned x, unsigned& nloc, unsigned& nx, const unsigned G) {
;     unsigned sum, cnt, mine, sp = 0u;
;     for (;;) {
;         sum = 0u; cnt = 0u; mine = 0u;
; #pragma unroll
;         for (unsigned j = 0; j < 16; ++j) { const unsigned c = xb_ld(&bar[XB_XCNT(j)]); sum += c; cnt += (c > 0u) ? 1u : 0u; mine = (j == x) ? c : mine; }
; __device__ __forceinline__ void xcd_barrier(const XcdBarrier& b) {
;     asm volatile("s_waitcnt vmcnt(0)" ::: "memory");
;     __syncthreads();
;     if (threadIdx.x == 0) {
;         unsigned* bar = b.bar;
;         __builtin_amdgcn_s_waitcnt(0);
;         unsigned nloc = b.st[0], nx = b.st[1];
;         if (nloc == 0u) { xcd_barrier_complete(bar, b.x, nloc, nx, b.G); b.st[0] = nloc; b.st[1] = nx; }
;         const unsigned old = xb_add(&bar[XB_XSUB(b.x)], 1u);
.LBB0_555:
	s_setprio 0
	s_waitcnt vmcnt(0)
	v_readlane_b32 s74, v232, 4
	v_readlane_b32 s75, v232, 5
	s_waitcnt vmcnt(0) lgkmcnt(0)
	s_barrier
	s_and_saveexec_b64 s[2:3], s[74:75]
	s_cbranch_execz .LBB0_607
	s_add_i32 s4, 0, 0x21108
	v_mov_b32_e32 v0, s4
	s_waitcnt vmcnt(0) expcnt(0) lgkmcnt(0)
	ds_read_b32 v2, v0
	s_add_i32 s4, 0, 0x2110c
	v_mov_b32_e32 v0, s4
	ds_read_b32 v0, v0
	s_waitcnt lgkmcnt(1)
	v_cmp_ne_u32_e32 vcc, 0, v2
	s_cbranch_vccnz .LBB0_571
	s_add_u32 s4, s68, 0x4200
	s_addc_u32 s5, s69, 0
	s_add_u32 s6, s68, 0x4400
	s_addc_u32 s7, s69, 0
	s_add_u32 s8, s68, 0x4500
	s_addc_u32 s9, s69, 0
	s_add_u32 s38, s68, 0x4600
	s_addc_u32 s39, s69, 0
	s_add_u32 s42, s68, 0x4700
	s_addc_u32 s43, s69, 0
	s_add_u32 s44, s68, 0x4800
	s_addc_u32 s45, s69, 0
	s_add_u32 s46, s68, 0x4900
	s_addc_u32 s47, s69, 0
	s_add_u32 s48, s68, 0x4a00
	s_addc_u32 s49, s69, 0
	s_add_u32 s50, s68, 0x4b00
	s_addc_u32 s51, s69, 0
	s_add_u32 s52, s68, 0x4c00
	s_addc_u32 s53, s69, 0
	s_add_u32 s54, s68, 0x4d00
	s_addc_u32 s55, s69, 0
	s_add_u32 s56, s68, 0x4e00
	s_addc_u32 s57, s69, 0
	s_add_u32 s58, s68, 0x4f00
	s_addc_u32 s59, s69, 0
	s_add_u32 s60, s68, 0x5000
	s_addc_u32 s61, s69, 0
	s_add_u32 s62, s68, 0x5100
	s_addc_u32 s63, s69, 0
	s_add_u32 s64, s68, 0x5200
	s_addc_u32 s65, s69, 0
	s_add_u32 s66, s68, 0x5300
	s_mov_b32 s22, s67
	s_mov_b64 s[28:29], s[68:69]
	s_addc_u32 s67, s69, 0
	s_mov_b32 s10, 1
	v_mov_b32_e32 v16, 0
	s_branch .LBB0_559
